# static s_setprio 1 for waves 4-7 during the attention phases (P3, P3b) on top of the own-unit epilogue prefetch
# baseline (speedup 1.0000x reference)
; #define LAS __attribute__((address_space(3)))
; #define PHASE_ARGS() const CAS Args* ap = ap0; OPAQUE(ap); int tid = wave * 64 + lane_id(); asm volatile("" : "+v"(tid)); const int lane = tid & 63; (void)lane; unsigned char* ws = as_global(ap->ws)
; __global__ void __launch_bounds__(512, 2) hybrid_fwd(Args a_unused) {
;     ...
;         { PHASE_ARGS(); const unsigned* ctl = (const unsigned*)(ws + WS_CTL); const bf16_t* H = (const bf16_t*)(ws + WS_H); bf16_t* U = (bf16_t*)(ws + WS_U);
;           LAS unsigned* lcnt = (LAS unsigned*)(lds + AL_CNT); LAS unsigned* lpre = lcnt + 1024; LAS unsigned* lwt = lpre + 1032;
;           { const unsigned n0 = ctl[2 * tid], n1 = ctl[2 * tid + 1]; lcnt[2 * tid] = n0; lcnt[2 * tid + 1] = n1;
;             const unsigned c0 = (n0 + 511u) >> 9, c1 = (n1 + 511u) >> 9; unsigned incl = c0 + c1;
; #pragma unroll
;             for (int o = 1; o < 64; o <<= 1) { const unsigned t = __shfl_up(incl, o); if (lane >= o) incl += t; }
;             if (lane == 63) lwt[wave] = incl;
;             __syncthreads();
;             unsigned off = incl - (c0 + c1);
;             for (int w = 0; w < wave; ++w) off += lwt[w];
;             lpre[2 * tid] = off; lpre[2 * tid + 1] = off + c0; if (tid == 511) lpre[1024] = off + c0 + c1;
;             __syncthreads(); }
.LBB0_349:
	s_or_b64 exec, exec, s[0:1]
	s_waitcnt lgkmcnt(0)
	s_barrier
	v_readfirstlane_b32 s98, v218
	s_cmp_lt_u32 s98, 0x100
	s_cbranch_scc1 .Lp3_noprio
	s_setprio 1
.Lp3_noprio:
	v_mov_b32_e32 v151, v218
	v_writelane_b32 v252, s22, 5
	s_load_dwordx2 s[0:1], s[22:23], 0x58
	v_lshlrev_b32_e32 v2, 1, v151
	v_ashrrev_i32_e32 v3, 31, v2
	v_and_b32_e32 v146, 63, v151
	v_cmp_ne_u32_e32 vcc, 0, v146
	s_waitcnt lgkmcnt(0)
	v_lshl_add_u64 v[2:3], v[2:3], 2, s[0:1]
	global_load_dwordx2 v[4:5], v[2:3], off
	v_cmp_gt_u32_e64 s[38:39], 8, v146
	s_mov_b64 s[72:73], s[0:1]
	v_cmp_gt_u32_e64 s[0:1], 32, v146
	v_cmp_lt_u32_e64 s[40:41], 7, v146
	s_mov_b64 s[78:79], s[0:1]
	v_writelane_b32 v252, s23, 6
	s_waitcnt vmcnt(0)
	v_add_u32_e32 v0, 0x1ff, v4
	v_add_u32_e32 v2, 0x1ff, v5
	v_lshrrev_b32_e32 v6, 9, v0
	v_lshrrev_b32_e32 v0, 9, v2
	v_add_u32_e32 v2, v0, v6
	ds_bpermute_b32 v3, v220, v2
	s_waitcnt lgkmcnt(0)
	v_cndmask_b32_e32 v3, 0, v3, vcc
	v_add_u32_e32 v3, v3, v2
	ds_bpermute_b32 v7, v221, v3
	v_cmp_lt_u32_e32 vcc, 1, v146
	s_waitcnt lgkmcnt(0)
	s_nop 0
	v_cndmask_b32_e32 v7, 0, v7, vcc
	v_add_u32_e32 v3, v7, v3
	ds_bpermute_b32 v7, v222, v3
	v_cmp_lt_u32_e32 vcc, 3, v146
	s_waitcnt lgkmcnt(0)
	s_nop 0
	v_cndmask_b32_e32 v7, 0, v7, vcc
	v_add_u32_e32 v3, v7, v3
	ds_bpermute_b32 v7, v223, v3
	v_cmp_lt_u32_e32 vcc, 15, v146
	s_waitcnt lgkmcnt(0)
	v_cndmask_b32_e64 v7, v7, 0, s[38:39]
	v_add_u32_e32 v3, v7, v3
	ds_bpermute_b32 v7, v224, v3
	s_waitcnt lgkmcnt(0)
	v_cndmask_b32_e32 v7, 0, v7, vcc
	v_add_u32_e32 v3, v7, v3
	ds_bpermute_b32 v8, v225, v3
	v_lshl_add_u32 v7, v151, 3, 0
	ds_write_b64 v7, v[4:5] offset:50176
	v_cmp_eq_u32_e32 vcc, 63, v146
	s_waitcnt lgkmcnt(1)
	v_cndmask_b32_e64 v4, v8, 0, s[0:1]
	v_add_u32_e32 v3, v4, v3
	s_and_saveexec_b64 s[18:19], vcc
	s_cbranch_execz .LBB0_351
	v_readlane_b32 s0, v253, 55
	s_nop 1
	v_mov_b32_e32 v4, s0
	ds_write_b32 v4, v3 offset:58400
